# v15
# baseline (speedup 1.0000x reference)
.LBB0_411:
	s_waitcnt vmcnt(8)
	v_readlane_b32 s68, v254, 63
	s_cmpk_gt_u32 s14, 0xff
	v_readlane_b32 s69, v255, 0
	s_cbranch_scc1 .LBB0_413
	s_barrier

.LBB0_449:
	v_lshl_add_u64 v[28:29], v[26:27], 0, s[38:39]
	global_load_dwordx4 v[100:103], v[28:29], off
	v_add_co_u32_e64 v104, s[0:1], s4, v28
	s_nop 1
	v_addc_co_u32_e64 v105, s[0:1], 0, v29, s[0:1]
	global_load_dwordx4 v[104:107], v[104:105], off
	s_mov_b32 s0, 0x24000
	v_add_co_u32_e64 v108, s[0:1], s0, v28
	s_nop 1
	v_addc_co_u32_e64 v109, s[0:1], 0, v29, s[0:1]
	global_load_dwordx4 v[108:111], v[108:109], off
	s_mov_b32 s0, 0x36000
	v_add_co_u32_e64 v112, s[0:1], s0, v28
	s_nop 1
	v_addc_co_u32_e64 v113, s[0:1], 0, v29, s[0:1]
	global_load_dwordx4 v[112:115], v[112:113], off
	s_mov_b32 s0, 0x48000
	v_add_co_u32_e64 v116, s[0:1], s0, v28
	s_nop 1
	v_addc_co_u32_e64 v117, s[0:1], 0, v29, s[0:1]
	global_load_dwordx4 v[116:119], v[116:117], off
	s_mov_b32 s0, 0x5a000
	v_add_co_u32_e64 v120, s[0:1], s0, v28
	s_nop 1
	v_addc_co_u32_e64 v121, s[0:1], 0, v29, s[0:1]
	global_load_dwordx4 v[120:123], v[120:121], off
	s_mov_b32 s0, 0x6c000
	v_add_co_u32_e64 v124, s[0:1], s0, v28
	s_nop 1
	v_addc_co_u32_e64 v125, s[0:1], 0, v29, s[0:1]
	global_load_dwordx4 v[124:127], v[124:125], off
	s_mov_b32 s0, 0x7e000
	v_add_co_u32_e64 v128, s[0:1], s0, v28
	s_nop 1
	v_addc_co_u32_e64 v129, s[0:1], 0, v29, s[0:1]
	global_load_dwordx4 v[128:131], v[128:129], off
	ds_read_b128 v[40:43], v31
	ds_read_b128 v[2:5], v31 offset:16
	s_add_u32 s38, s38, 0x90000
	s_addc_u32 s39, s39, 0
	s_cmp_eq_u32 s38, 0x480000
	s_waitcnt vmcnt(7) lgkmcnt(1)
	v_pk_fma_f32 v[32:33], v[102:103], v[40:41], v[8:9] op_sel_hi:[1,0,1]
	v_pk_fma_f32 v[44:45], v[100:101], v[40:41], v[6:7] op_sel_hi:[1,0,1]
	ds_read_b128 v[6:9], v31 offset:8192
	s_waitcnt lgkmcnt(0)
	v_pk_fma_f32 v[46:47], v[102:103], v[6:7], v[12:13] op_sel_hi:[1,0,1]
	v_pk_fma_f32 v[48:49], v[100:101], v[6:7], v[10:11] op_sel_hi:[1,0,1]
	ds_read_b128 v[10:13], v31 offset:16384
	s_waitcnt lgkmcnt(0)
	v_pk_fma_f32 v[36:37], v[100:101], v[10:11], v[14:15] op_sel_hi:[1,0,1]
	v_pk_fma_f32 v[38:39], v[102:103], v[10:11], v[16:17] op_sel_hi:[1,0,1]
	s_waitcnt vmcnt(6)
	v_pk_fma_f32 v[44:45], v[104:105], v[40:41], v[44:45] op_sel:[0,1,0]
	v_pk_fma_f32 v[32:33], v[106:107], v[40:41], v[32:33] op_sel:[0,1,0]
	v_pk_fma_f32 v[40:41], v[104:105], v[6:7], v[48:49] op_sel:[0,1,0]
	v_pk_fma_f32 v[36:37], v[104:105], v[10:11], v[36:37] op_sel:[0,1,0]
	v_pk_fma_f32 v[6:7], v[106:107], v[6:7], v[46:47] op_sel:[0,1,0]
	v_pk_fma_f32 v[10:11], v[106:107], v[10:11], v[38:39] op_sel:[0,1,0]
	s_waitcnt vmcnt(5)
	v_pk_fma_f32 v[38:39], v[108:109], v[42:43], v[44:45] op_sel_hi:[1,0,1]
	v_pk_fma_f32 v[40:41], v[108:109], v[8:9], v[40:41] op_sel_hi:[1,0,1]
	v_pk_fma_f32 v[36:37], v[108:109], v[12:13], v[36:37] op_sel_hi:[1,0,1]
	v_pk_fma_f32 v[32:33], v[110:111], v[42:43], v[32:33] op_sel_hi:[1,0,1]
	v_pk_fma_f32 v[6:7], v[110:111], v[8:9], v[6:7] op_sel_hi:[1,0,1]
	v_pk_fma_f32 v[10:11], v[110:111], v[12:13], v[10:11] op_sel_hi:[1,0,1]
	v_mov_b32_e32 v8, v43
	s_waitcnt vmcnt(4)
	v_pk_fma_f32 v[32:33], v[114:115], v[8:9], v[32:33] op_sel_hi:[1,0,1]
	v_pk_fma_f32 v[38:39], v[112:113], v[8:9], v[38:39] op_sel_hi:[1,0,1]
	v_mov_b32_e32 v8, v9
	v_pk_fma_f32 v[42:43], v[114:115], v[8:9], v[6:7] op_sel_hi:[1,0,1]
	v_mov_b32_e32 v6, v13
	v_pk_fma_f32 v[44:45], v[114:115], v[6:7], v[10:11] op_sel_hi:[1,0,1]
	v_pk_fma_f32 v[36:37], v[112:113], v[6:7], v[36:37] op_sel_hi:[1,0,1]
	v_pk_fma_f32 v[40:41], v[112:113], v[8:9], v[40:41] op_sel_hi:[1,0,1]
	ds_read_b128 v[10:13], v31 offset:8208
	ds_read_b128 v[14:17], v31 offset:16400
	v_add_u32_e32 v31, 32, v31
	s_waitcnt vmcnt(3)
	v_pk_fma_f32 v[38:39], v[116:117], v[2:3], v[38:39] op_sel_hi:[1,0,1]
	s_waitcnt lgkmcnt(1)
	v_pk_fma_f32 v[40:41], v[116:117], v[10:11], v[40:41] op_sel_hi:[1,0,1]
	s_waitcnt lgkmcnt(0)
	v_pk_fma_f32 v[36:37], v[116:117], v[14:15], v[36:37] op_sel_hi:[1,0,1]
	v_pk_fma_f32 v[32:33], v[118:119], v[2:3], v[32:33] op_sel_hi:[1,0,1]
	v_pk_fma_f32 v[42:43], v[118:119], v[10:11], v[42:43] op_sel_hi:[1,0,1]
	v_pk_fma_f32 v[44:45], v[118:119], v[14:15], v[44:45] op_sel_hi:[1,0,1]
	s_waitcnt vmcnt(2)
	v_pk_fma_f32 v[32:33], v[122:123], v[2:3], v[32:33] op_sel:[0,1,0]
	v_pk_fma_f32 v[2:3], v[120:121], v[2:3], v[38:39] op_sel:[0,1,0]
	v_pk_fma_f32 v[38:39], v[122:123], v[10:11], v[42:43] op_sel:[0,1,0]
	v_pk_fma_f32 v[10:11], v[120:121], v[10:11], v[40:41] op_sel:[0,1,0]
	v_pk_fma_f32 v[40:41], v[122:123], v[14:15], v[44:45] op_sel:[0,1,0]
	v_pk_fma_f32 v[14:15], v[120:121], v[14:15], v[36:37] op_sel:[0,1,0]
	s_waitcnt vmcnt(1)
	v_pk_fma_f32 v[2:3], v[124:125], v[4:5], v[2:3] op_sel_hi:[1,0,1]
	v_pk_fma_f32 v[10:11], v[124:125], v[12:13], v[10:11] op_sel_hi:[1,0,1]
	v_pk_fma_f32 v[14:15], v[124:125], v[16:17], v[14:15] op_sel_hi:[1,0,1]
	v_pk_fma_f32 v[42:43], v[126:127], v[12:13], v[38:39] op_sel_hi:[1,0,1]
	v_pk_fma_f32 v[32:33], v[126:127], v[4:5], v[32:33] op_sel_hi:[1,0,1]
	v_mov_b32_e32 v4, v5
	v_pk_fma_f32 v[40:41], v[126:127], v[16:17], v[40:41] op_sel_hi:[1,0,1]
	s_waitcnt vmcnt(0)
	v_pk_fma_f32 v[6:7], v[128:129], v[4:5], v[2:3] op_sel_hi:[1,0,1]
	v_mov_b32_e32 v2, v13
	v_pk_fma_f32 v[12:13], v[130:131], v[2:3], v[42:43] op_sel_hi:[1,0,1]
	v_pk_fma_f32 v[10:11], v[128:129], v[2:3], v[10:11] op_sel_hi:[1,0,1]
	v_mov_b32_e32 v2, v17
	v_pk_fma_f32 v[8:9], v[130:131], v[4:5], v[32:33] op_sel_hi:[1,0,1]
	v_pk_fma_f32 v[16:17], v[130:131], v[2:3], v[40:41] op_sel_hi:[1,0,1]
	v_pk_fma_f32 v[14:15], v[128:129], v[2:3], v[14:15] op_sel_hi:[1,0,1]
	s_cbranch_scc0 .LBB0_449
	s_barrier
	ds_write_b128 v21, v[6:9] offset:24576
	ds_write_b128 v21, v[10:13] offset:24832
	ds_write_b128 v21, v[14:17] offset:25088
	s_waitcnt lgkmcnt(0)
	s_barrier
	s_and_saveexec_b64 s[0:1], vcc
	s_cbranch_execz .LBB0_447
	v_mov_b32_e32 v2, 0
	s_mov_b32 s9, 0

.LBB0_454:
	v_and_b32_e32 v198, 63, v34
	v_ashrrev_i32_e32 v199, 6, v34
	s_sub_i32 s5, s96, s22
	s_add_i32 s5, s5, -1
	s_cmpk_gt_i32 s5, 0x9f
	s_barrier
	s_cbranch_scc1 .LBB0_483
	s_mov_b32 s0, 0x3e0f83e1
	v_mul_hi_i32 v0, v34, s0
	v_lshrrev_b32_e32 v2, 31, v0
	v_ashrrev_i32_e32 v0, 3, v0
	v_add_u32_e32 v200, v0, v2
	v_lshl_add_u32 v0, v200, 5, v200
	v_sub_u32_e32 v5, v34, v0
	v_add_u32_e32 v0, -16, v5
	v_cmp_gt_i32_e32 vcc, 17, v5
	v_ashrrev_i32_e32 v19, 31, v18
	v_readlane_b32 s44, v251, 1
	s_movk_i32 s0, 0xa0
	v_cndmask_b32_e32 v8, v0, v5, vcc
	v_lshlrev_b32_e32 v0, 2, v198
	v_lshlrev_b64 v[2:3], 2, v[18:19]
	v_readlane_b32 s46, v251, 3
	v_readlane_b32 s47, v251, 4
	v_readlane_b32 s48, v251, 5
	v_readlane_b32 s49, v251, 6
	v_cmp_ne_u32_e64 s[38:39], 0, v5
	v_cmp_lt_i32_e64 s[40:41], 16, v5
	v_lshlrev_b32_e32 v5, 2, v5
	v_mul_lo_u32 v9, v200, s0
	v_readlane_b32 s60, v251, 45
	v_lshl_add_u64 v[6:7], s[46:47], 0, v[2:3]
	v_add3_u32 v201, 0, v9, v5
	v_cvt_f32_i32_e32 v202, v8
	v_lshl_add_u64 v[8:9], s[48:49], 0, v[2:3]
	v_or_b32_e32 v2, 0x1d00, v0
	v_mov_b32_e32 v3, v1
	v_readlane_b32 s68, v251, 53
	v_readlane_b32 s69, v251, 54
	v_readlane_b32 s72, v251, 57
	v_readlane_b32 s73, v251, 58
	v_lshl_add_u64 v[66:67], s[68:69], 0, v[2:3]
	v_and_b32_e32 v5, 0x3fffffc0, v34
	v_lshl_add_u64 v[68:69], s[72:73], 0, v[2:3]
	v_mul_lo_u32 v2, v199, s0
	v_lshl_add_u64 v[90:91], s[72:73], 0, v[0:1]
	s_mov_b64 s[0:1], 0x2100
	v_lshl_add_u64 v[92:93], v[90:91], 0, s[0:1]
	s_mov_b64 s[0:1], 0x2200
	v_lshl_add_u64 v[94:95], v[90:91], 0, s[0:1]
	s_mov_b64 s[0:1], 0x2300
	v_lshl_add_u64 v[96:97], v[90:91], 0, s[0:1]
	s_mov_b64 s[0:1], 0x2400
	v_lshl_add_u64 v[98:99], v[90:91], 0, s[0:1]
	s_mov_b64 s[0:1], 0x2500
	v_lshl_add_u64 v[100:101], v[90:91], 0, s[0:1]
	s_mov_b64 s[0:1], 0x2600
	v_lshl_add_u64 v[102:103], v[90:91], 0, s[0:1]
	s_mov_b64 s[0:1], 0x2700
	v_lshl_add_u64 v[104:105], v[90:91], 0, s[0:1]
	s_mov_b64 s[0:1], 0x2800
	v_lshl_add_u64 v[106:107], v[90:91], 0, s[0:1]
	s_mov_b64 s[0:1], 0x2900
	v_lshl_add_u64 v[108:109], v[90:91], 0, s[0:1]
	s_mov_b64 s[0:1], 0x2a00
	v_lshl_add_u64 v[110:111], v[90:91], 0, s[0:1]
	s_mov_b64 s[0:1], 0x2b00
	v_lshl_add_u64 v[112:113], v[90:91], 0, s[0:1]
	s_mov_b64 s[0:1], 0x2c00
	v_lshl_add_u64 v[114:115], v[90:91], 0, s[0:1]
	s_mov_b64 s[0:1], 0x2d00
	v_lshl_add_u64 v[116:117], v[90:91], 0, s[0:1]
	s_mov_b64 s[0:1], 0x2e00
	v_lshl_add_u64 v[118:119], v[90:91], 0, s[0:1]
	s_mov_b64 s[0:1], 0x2f00
	v_lshl_add_u64 v[120:121], v[90:91], 0, s[0:1]
	s_mov_b64 s[0:1], 0x3000
	v_lshl_add_u64 v[122:123], v[90:91], 0, s[0:1]
	s_mov_b64 s[0:1], 0x3100
	v_lshl_add_u64 v[124:125], v[90:91], 0, s[0:1]
	s_mov_b64 s[0:1], 0x3200
	v_lshl_add_u64 v[126:127], v[90:91], 0, s[0:1]
	s_mov_b64 s[0:1], 0x3300
	v_lshl_add_u64 v[128:129], v[90:91], 0, s[0:1]
	s_mov_b64 s[0:1], 0x3400
	v_lshl_add_u64 v[130:131], v[90:91], 0, s[0:1]
	s_mov_b64 s[0:1], 0x3500
	v_lshl_add_u64 v[132:133], v[90:91], 0, s[0:1]
	s_mov_b64 s[0:1], 0x3600
	v_lshl_add_u64 v[134:135], v[90:91], 0, s[0:1]
	s_mov_b64 s[0:1], 0x3700
	v_lshl_add_u64 v[136:137], v[90:91], 0, s[0:1]
	s_mov_b64 s[0:1], 0x3800
	v_lshl_add_u64 v[138:139], v[90:91], 0, s[0:1]
	s_mov_b64 s[0:1], 0x3900
	v_lshl_add_u64 v[140:141], v[90:91], 0, s[0:1]
	s_mov_b64 s[0:1], 0x3a00
	v_lshl_add_u64 v[142:143], v[90:91], 0, s[0:1]
	s_mov_b64 s[0:1], 0x3b00
	v_lshl_add_u64 v[144:145], v[90:91], 0, s[0:1]
	s_mov_b64 s[0:1], 0x3c00
	v_lshl_add_u64 v[146:147], v[90:91], 0, s[0:1]
	s_mov_b64 s[0:1], 0x3d00
	v_lshl_add_u64 v[148:149], v[90:91], 0, s[0:1]
	s_mov_b64 s[0:1], 0x3e00
	v_or_b32_e32 v4, 0x1000, v0
	v_or_b32_e32 v16, 0x1100, v0
	v_or_b32_e32 v22, 0x1200, v0
	v_or_b32_e32 v26, 0x1300, v0
	v_or_b32_e32 v30, 0x1400, v0
	v_or_b32_e32 v36, 0x1500, v0
	v_or_b32_e32 v40, 0x1600, v0
	v_or_b32_e32 v44, 0x1700, v0
	v_or_b32_e32 v48, 0x1800, v0
	v_or_b32_e32 v52, 0x1900, v0
	v_or_b32_e32 v56, 0x1a00, v0
	v_or_b32_e32 v60, 0x1b00, v0
	v_or_b32_e32 v64, 0x1c00, v0
	v_lshl_add_u32 v203, v5, 2, 0
	v_mov_b32_e32 v5, v1
	v_mov_b32_e32 v17, v1
	v_mov_b32_e32 v23, v1
	v_mov_b32_e32 v27, v1
	v_mov_b32_e32 v31, v1
	v_mov_b32_e32 v37, v1
	v_mov_b32_e32 v41, v1
	v_mov_b32_e32 v45, v1
	v_mov_b32_e32 v49, v1
	v_mov_b32_e32 v53, v1
	v_mov_b32_e32 v57, v1
	v_mov_b32_e32 v61, v1
	v_mov_b32_e32 v65, v1
	v_or_b32_e32 v72, 0x1e00, v0
	v_mov_b32_e32 v73, v1
	v_or_b32_e32 v76, 0x1f00, v0
	v_mov_b32_e32 v77, v1
	v_or_b32_e32 v80, 0x2000, v0
	v_mov_b32_e32 v81, v1
	v_readlane_b32 s66, v251, 51
	v_readlane_b32 s67, v251, 52
	v_readlane_b32 s74, v251, 59
	v_readlane_b32 s75, v251, 60
	v_lshl_add_u64 v[150:151], v[90:91], 0, s[0:1]
	s_mov_b64 s[0:1], 0x3f00
	v_readlane_b32 s45, v251, 2
	v_readlane_b32 s70, v251, 55
	v_readlane_b32 s71, v251, 56
	v_lshl_add_u64 v[10:11], s[68:69], 0, v[4:5]
	v_lshl_add_u64 v[14:15], s[68:69], 0, v[16:17]
	v_lshl_add_u64 v[20:21], s[68:69], 0, v[22:23]
	v_lshl_add_u64 v[24:25], s[68:69], 0, v[26:27]
	v_lshl_add_u64 v[28:29], s[68:69], 0, v[30:31]
	v_lshl_add_u64 v[32:33], s[68:69], 0, v[36:37]
	v_lshl_add_u64 v[38:39], s[68:69], 0, v[40:41]
	v_lshl_add_u64 v[42:43], s[68:69], 0, v[44:45]
	v_lshl_add_u64 v[46:47], s[68:69], 0, v[48:49]
	v_lshl_add_u64 v[50:51], s[68:69], 0, v[52:53]
	v_lshl_add_u64 v[54:55], s[68:69], 0, v[56:57]
	v_lshl_add_u64 v[58:59], s[68:69], 0, v[60:61]
	v_lshl_add_u64 v[62:63], s[68:69], 0, v[64:65]
	v_lshl_add_u64 v[70:71], s[68:69], 0, v[72:73]
	v_lshl_add_u64 v[74:75], s[68:69], 0, v[76:77]
	v_lshl_add_u64 v[78:79], s[68:69], 0, v[80:81]
	v_lshl_add_u64 v[86:87], s[74:75], 0, v[0:1]
	v_readlane_b32 s74, v254, 51
	v_lshl_add_u64 v[88:89], s[68:69], 0, v[0:1]
	v_readlane_b32 s68, v254, 29
	v_readlane_b32 s66, v252, 58
	v_lshl_add_u64 v[152:153], v[90:91], 0, s[0:1]
	s_movk_i32 s0, 0x108
	v_lshl_add_u64 v[12:13], s[72:73], 0, v[4:5]
	v_lshl_add_u64 v[16:17], s[72:73], 0, v[16:17]
	v_lshl_add_u64 v[22:23], s[72:73], 0, v[22:23]
	v_lshl_add_u64 v[26:27], s[72:73], 0, v[26:27]
	v_lshl_add_u64 v[30:31], s[72:73], 0, v[30:31]
	v_lshl_add_u64 v[36:37], s[72:73], 0, v[36:37]
	v_lshl_add_u64 v[40:41], s[72:73], 0, v[40:41]
	v_lshl_add_u64 v[44:45], s[72:73], 0, v[44:45]
	v_lshl_add_u64 v[48:49], s[72:73], 0, v[48:49]
	v_lshl_add_u64 v[52:53], s[72:73], 0, v[52:53]
	v_lshl_add_u64 v[56:57], s[72:73], 0, v[56:57]
	v_lshl_add_u64 v[60:61], s[72:73], 0, v[60:61]
	v_lshl_add_u64 v[64:65], s[72:73], 0, v[64:65]
	v_lshl_add_u64 v[72:73], s[72:73], 0, v[72:73]
	v_lshl_add_u64 v[76:77], s[72:73], 0, v[76:77]
	v_lshl_add_u64 v[80:81], s[72:73], 0, v[80:81]
	v_add_u32_e32 v204, 0, v2
	v_add_u32_e32 v205, 0, v18
	v_lshl_add_u64 v[82:83], s[70:71], 0, v[0:1]
	v_lshl_add_u64 v[84:85], s[44:45], 0, v[0:1]
	v_readlane_b32 s75, v254, 52
	v_readlane_b32 s69, v254, 30
	v_readlane_b32 s67, v252, 59
	s_sub_i32 s5, s96, s22
	s_add_i32 s5, s5, -1
	v_cmp_gt_i32_e64 s[42:43], s0, v34
	v_readlane_b32 s50, v251, 7
	v_readlane_b32 s51, v251, 8
	v_readlane_b32 s61, v251, 46
	v_readlane_b32 s62, v251, 47
	v_readlane_b32 s63, v251, 48
	v_readlane_b32 s64, v251, 49
	v_readlane_b32 s65, v251, 50
